# v37 + late weight f32->bf16 transposes moved out of P0 and piggybacked on attention units (wide loads after the unit prologue wait, permlane-swap transposition + stores at unit end)
# speedup vs baseline: 1.0032x; 1.0004x over previous
.Lp3_attn:
	v_mov_b32_e32 v247, s6
	s_cmpk_gt_i32 s6, 0x16f
	s_mov_b64 s[0:1], -1
	s_cbranch_scc0 .LBB0_516
	s_cmpk_gt_u32 s6, 0x2ef
	s_cbranch_scc0 .LBB0_510
	s_add_i32 s0, s6, 0xfffffd10
	s_lshr_b32 s0, s0, 4
	s_sub_i32 s79, 16, s0
	s_bfe_u32 s13, s6, 0x10003
	s_and_b32 s12, s6, 7
	s_mov_b64 s[0:1], 0

.LBB0_550:
	s_or_b64 exec, exec, s[0:1]
	v_add_u32_e32 v0, 1, v128
	v_cvt_f32_u32_e32 v0, v0
	v_mov_b32_e32 v95, v97
	v_mov_b32_e32 v97, v103
	v_mov_b32_e32 v79, v85
	v_exp_f32_e64 v0, -v0
	v_mov_b32_e32 v85, v101
	v_mov_b32_e32 v87, v93
	v_mov_b32_e32 v93, v113
	v_mul_f32_e32 v118, 0x3fb8aa3b, v0
	v_add_f32_e32 v0, v99, v102
	v_fmamk_f32 v0, v0, 0x3c800000, v154
	v_rsq_f32_e32 v0, v0
	v_mov_b32_e32 v99, v67
	v_mov_b32_e32 v77, v89
	v_mov_b32_e32 v89, v117
	v_mul_f32_e32 v0, 0x3e38aa3b, v0
	s_waitcnt vmcnt(0)
	v_readfirstlane_b32 s0, v247
	v_readfirstlane_b32 s1, v202
	s_lshr_b32 s1, s1, 6
	s_mul_i32 s2, s0, 5
	s_add_i32 s2, s2, s1
	s_lshr_b32 s3, s0, 2
	s_addk_i32 s3, 0x1400
	s_cmp_lt_u32 s1, 5
	s_cselect_b32 s2, s2, s3
	s_cselect_b32 s4, 1, 0
	s_and_b32 s3, s0, 3
	s_cmp_eq_u32 s3, 0
	s_cselect_b32 s3, 1, 0
	s_cmp_eq_u32 s1, 5
	s_cselect_b32 s3, s3, 0
	s_or_b32 s4, s4, s3
	s_cmp_eq_u32 s88, 0x100
	s_cselect_b32 s4, s4, 0
	v_mov_b32_e32 v246, s4
	s_cmp_eq_u32 s4, 0
	s_cbranch_scc1 .Llwp_a_end
	s_and_b32 s1, s2, 1
	s_lshr_b32 s0, s2, 1
	v_mov_b32_e32 v236, s0
	v_mov_b32_e32 v237, 0x680
	v_mov_b32_e32 v238, 0x4
	v_mov_b32_e32 v239, 0xa
	v_mov_b32_e32 v240, 0x1c00000
	v_mov_b32_e32 v241, 0x1000
	v_mov_b32_e32 v242, 0x78
	v_cmp_le_u32_e32 vcc, 0x680, v236
	v_mov_b32_e32 v243, 0x280
	v_cndmask_b32_e32 v237, v243, v237, vcc
	v_cndmask_b32_e32 v238, 6, v238, vcc
	v_cndmask_b32_e32 v239, 12, v239, vcc
	v_mov_b32_e32 v243, 0x1400000
	v_cndmask_b32_e32 v240, v243, v240, vcc
	v_mov_b32_e32 v243, 0x400
	v_cndmask_b32_e32 v241, v243, v241, vcc
	v_mov_b32_e32 v243, 0x70
	v_cndmask_b32_e32 v242, v243, v242, vcc
	v_cmp_le_u32_e32 vcc, 0x280, v236
	v_mov_b32_e32 v243, 0x180
	v_cndmask_b32_e32 v237, v243, v237, vcc
	v_cndmask_b32_e32 v238, 4, v238, vcc
	v_cndmask_b32_e32 v239, 10, v239, vcc
	v_mov_b32_e32 v243, 0x1200000
	v_cndmask_b32_e32 v240, v243, v240, vcc
	v_mov_b32_e32 v243, 0x400
	v_cndmask_b32_e32 v241, v243, v241, vcc
	v_mov_b32_e32 v243, 0x60
	v_cndmask_b32_e32 v242, v243, v242, vcc
	v_cmp_le_u32_e32 vcc, 0x180, v236
	v_mov_b32_e32 v243, 0x80
	v_cndmask_b32_e32 v237, v243, v237, vcc
	v_cndmask_b32_e32 v238, 4, v238, vcc
	v_cndmask_b32_e32 v239, 10, v239, vcc
	v_mov_b32_e32 v243, 0xf00400
	v_cndmask_b32_e32 v240, v243, v240, vcc
	v_mov_b32_e32 v243, 0x600
	v_cndmask_b32_e32 v241, v243, v241, vcc
	v_mov_b32_e32 v243, 0x58
	v_cndmask_b32_e32 v242, v243, v242, vcc
	v_cmp_le_u32_e32 vcc, 0x80, v236
	v_cndmask_b32_e32 v237, 0, v237, vcc
	v_cndmask_b32_e32 v238, 4, v238, vcc
	v_cndmask_b32_e32 v239, 10, v239, vcc
	v_mov_b32_e32 v243, 0xf00000
	v_cndmask_b32_e32 v240, v243, v240, vcc
	v_mov_b32_e32 v243, 0x600
	v_cndmask_b32_e32 v241, v243, v241, vcc
	v_mov_b32_e32 v243, 0x50
	v_cndmask_b32_e32 v242, v243, v242, vcc
	v_sub_u32_e32 v243, v236, v237
	v_lshrrev_b32_e32 v244, v238, v243
	v_lshlrev_b32_e32 v245, v238, v244
	v_sub_u32_e32 v245, v243, v245
	s_lshl_b32 s1, s1, 5
	v_lshl_add_u32 v192, v244, 6, s1
	v_and_b32_e32 v193, 63, v202
	v_lshrrev_b32_e32 v195, 4, v193
	v_and_b32_e32 v201, 15, v193
	v_add_u32_e32 v193, v192, v195
	v_add_u32_e32 v203, 2, v239
	v_lshlrev_b32_e32 v193, v203, v193
	v_lshl_add_u32 v193, v245, 8, v193
	v_lshl_add_u32 v193, v201, 4, v193
	v_lshlrev_b32_e64 v203, v239, 16
	v_readlane_b32 s6, v248, 14
	v_readlane_b32 s7, v248, 15
	v_readfirstlane_b32 s4, v203
	v_readfirstlane_b32 s5, v242
	v_lshlrev_b32_e32 v203, 6, v245
	v_lshl_add_u32 v203, v201, 2, v203
	v_add_u32_e32 v203, v203, v195
	v_mul_lo_u32 v203, v203, v241
	v_add_u32_e32 v203, v203, v192
	v_lshl_add_u32 v244, v203, 1, v240
	v_and_b32_e32 v245, 0x3ff, v192
	v_add_u32_e32 v245, v245, v195
	v_lshlrev_b32_e32 v245, 2, v245
	s_load_dwordx2 s[2:3], s[6:7], s5
	s_waitcnt lgkmcnt(0)
	global_load_dwordx4 v[204:207], v193, s[2:3]
	s_add_u32 s2, s2, s4
	s_addc_u32 s3, s3, 0
	global_load_dwordx4 v[208:211], v193, s[2:3]
	s_add_u32 s2, s2, s4
	s_addc_u32 s3, s3, 0
	global_load_dwordx4 v[212:215], v193, s[2:3]
	s_add_u32 s2, s2, s4
	s_addc_u32 s3, s3, 0
	global_load_dwordx4 v[216:219], v193, s[2:3]
	s_add_u32 s2, s2, s4
	s_addc_u32 s3, s3, 0
	global_load_dwordx4 v[220:223], v193, s[2:3]
	s_add_u32 s2, s2, s4
	s_addc_u32 s3, s3, 0
	global_load_dwordx4 v[224:227], v193, s[2:3]
	s_add_u32 s2, s2, s4
	s_addc_u32 s3, s3, 0
	global_load_dwordx4 v[228:231], v193, s[2:3]
	s_add_u32 s2, s2, s4
	s_addc_u32 s3, s3, 0
	global_load_dwordx4 v[232:235], v193, s[2:3]
	s_cmp_eq_u32 s5, 0x70
	s_cbranch_scc0 .Llwp_a_end
	s_load_dwordx2 s[2:3], s[6:7], 0x68
	v_mov_b32_e32 v246, 3
	s_waitcnt lgkmcnt(0)
	global_load_dword v236, v245, s[2:3]
	global_load_dword v237, v245, s[2:3] offset:16
	global_load_dword v238, v245, s[2:3] offset:32
	global_load_dword v239, v245, s[2:3] offset:48
	global_load_dword v240, v245, s[2:3] offset:64
	global_load_dword v241, v245, s[2:3] offset:80
	global_load_dword v242, v245, s[2:3] offset:96
	global_load_dword v243, v245, s[2:3] offset:112
.Llwp_a_end:
	v_pk_mul_f32 v[34:35], v[0:1], v[98:99] op_sel_hi:[0,1]
	v_pk_mul_f32 v[30:31], v[30:31], v[34:35]
	v_pk_mul_f32 v[34:35], v[0:1], v[96:97] op_sel_hi:[0,1]
	v_pk_mul_f32 v[32:33], v[32:33], v[34:35]
	v_pk_mul_f32 v[34:35], v[0:1], v[84:85] op_sel_hi:[0,1]
	v_pk_mul_f32 v[26:27], v[26:27], v[34:35]
	v_mov_b32_e32 v75, v109
	v_cvt_pk_bf16_f32 v84, v26, v27
	v_pk_mul_f32 v[26:27], v[0:1], v[94:95] op_sel_hi:[0,1]
	v_pk_mul_f32 v[22:23], v[22:23], v[26:27]
	v_pk_mul_f32 v[26:27], v[0:1], v[92:93] op_sel_hi:[0,1]
	v_pk_mul_f32 v[24:25], v[24:25], v[26:27]
	v_pk_mul_f32 v[26:27], v[0:1], v[88:89] op_sel_hi:[0,1]
	v_pk_mul_f32 v[18:19], v[18:19], v[26:27]
	v_mov_b32_e32 v71, v105
	v_cvt_pk_bf16_f32 v88, v18, v19
	v_pk_mul_f32 v[18:19], v[0:1], v[90:91] op_sel_hi:[0,1]
	v_pk_mul_f32 v[14:15], v[14:15], v[18:19]
	v_pk_mul_f32 v[18:19], v[0:1], v[80:81] op_sel_hi:[0,1]
	v_pk_mul_f32 v[16:17], v[16:17], v[18:19]
	v_pk_mul_f32 v[18:19], v[0:1], v[78:79] op_sel_hi:[0,1]
	v_pk_mul_f32 v[10:11], v[10:11], v[18:19]
	v_mov_b32_e32 v83, v111
	v_cvt_pk_bf16_f32 v92, v10, v11
	v_pk_mul_f32 v[10:11], v[0:1], v[74:75] op_sel_hi:[0,1]
	v_pk_mul_f32 v[6:7], v[6:7], v[10:11]
	v_pk_mul_f32 v[10:11], v[0:1], v[72:73] op_sel_hi:[0,1]
	v_pk_mul_f32 v[8:9], v[8:9], v[10:11]
	v_pk_mul_f32 v[10:11], v[0:1], v[70:71] op_sel_hi:[0,1]
	v_lshlrev_b32_e32 v119, 2, v170
	v_pk_mul_f32 v[34:35], v[0:1], v[82:83] op_sel_hi:[0,1]
	v_pk_mul_f32 v[26:27], v[0:1], v[86:87] op_sel_hi:[0,1]
	v_pk_mul_f32 v[18:19], v[0:1], v[76:77] op_sel_hi:[0,1]
	v_pk_mul_f32 v[2:3], v[2:3], v[10:11]
	v_pk_mul_f32 v[10:11], v[0:1], v[68:69] op_sel_hi:[0,1]
	v_or_b32_e32 v0, 1, v119
	v_cvt_pk_bf16_f32 v96, v2, v3
	v_cvt_f32_ubyte0_e32 v2, v119
	v_cvt_f32_ubyte0_e32 v3, v0
	v_pk_mul_f32 v[28:29], v[28:29], v[34:35]
	v_pk_mul_f32 v[34:35], v[118:119], v[2:3] op_sel_hi:[0,1]
	v_or_b32_e32 v0, 3, v119
	v_or_b32_e32 v2, 2, v119
	v_cvt_f32_ubyte0_e32 v3, v0
	v_cvt_f32_ubyte0_e32 v2, v2
	v_pk_mul_f32 v[36:37], v[118:119], v[2:3] op_sel_hi:[0,1]
	v_or_b32_e32 v0, 9, v119
	v_or_b32_e32 v2, 8, v119
	v_cvt_f32_ubyte0_e32 v3, v0
	v_cvt_f32_ubyte0_e32 v2, v2
	v_pk_mul_f32 v[38:39], v[118:119], v[2:3] op_sel_hi:[0,1]
	v_or_b32_e32 v0, 11, v119
	v_or_b32_e32 v2, 10, v119
	v_cvt_f32_ubyte0_e32 v3, v0
	v_cvt_f32_ubyte0_e32 v2, v2
	v_or_b32_e32 v0, 17, v119
	v_or_b32_e32 v98, 16, v119
	v_pk_mul_f32 v[40:41], v[118:119], v[2:3] op_sel_hi:[0,1]
	v_cvt_f32_ubyte0_e32 v3, v0
	v_cvt_f32_ubyte0_e32 v2, v98
	v_pk_mul_f32 v[42:43], v[118:119], v[2:3] op_sel_hi:[0,1]
	v_or_b32_e32 v0, 19, v119
	v_or_b32_e32 v2, 18, v119
	v_cvt_f32_ubyte0_e32 v3, v0
	v_cvt_f32_ubyte0_e32 v2, v2
	v_pk_mul_f32 v[44:45], v[118:119], v[2:3] op_sel_hi:[0,1]
	v_or_b32_e32 v0, 25, v119
	v_or_b32_e32 v2, 24, v119
	v_cvt_f32_ubyte0_e32 v3, v0
	v_cvt_f32_ubyte0_e32 v2, v2
	v_or_b32_e32 v0, 27, v119
	v_pk_mul_f32 v[46:47], v[118:119], v[2:3] op_sel_hi:[0,1]
	v_cvt_f32_ubyte0_e32 v3, v0
	v_subrev_u32_e32 v0, 31, v66
	v_and_b32_e32 v172, 31, v106
	v_lshlrev_b32_e32 v173, 3, v170
	v_or_b32_e32 v2, 26, v119
	v_ashrrev_i32_e32 v0, 4, v0
	s_cmp_gt_u32 s79, 15
	v_and_b32_e32 v107, 63, v106
	v_pk_mul_f32 v[20:21], v[20:21], v[26:27]
	v_pk_mul_f32 v[12:13], v[12:13], v[18:19]
	v_pk_mul_f32 v[4:5], v[4:5], v[10:11]
	v_cvt_f32_ubyte0_e32 v2, v2
	v_sub_u32_e32 v103, v0, v119
	s_cselect_b64 s[4:5], -1, 0
	s_cmp_lt_u32 s79, 16
	v_mad_u32_u24 v0, v172, s34, v173
	v_cvt_pk_bf16_f32 v82, v30, v31
	v_cvt_pk_bf16_f32 v83, v32, v33
	v_cvt_pk_bf16_f32 v85, v28, v29
	v_cvt_pk_bf16_f32 v86, v22, v23
	v_cvt_pk_bf16_f32 v87, v24, v25
	v_cvt_pk_bf16_f32 v89, v20, v21
	v_cvt_pk_bf16_f32 v90, v14, v15
	v_cvt_pk_bf16_f32 v91, v16, v17
	v_cvt_pk_bf16_f32 v93, v12, v13
	v_cvt_pk_bf16_f32 v94, v6, v7
	v_cvt_pk_bf16_f32 v95, v8, v9
	v_cvt_pk_bf16_f32 v97, v4, v5
	v_pk_mul_f32 v[48:49], v[118:119], v[2:3] op_sel_hi:[0,1]
	s_cselect_b64 s[6:7], -1, 0
	v_mul_f32_e32 v99, 0x44000000, v118
	v_cmp_gt_u32_e64 s[0:1], 32, v107
	s_cmp_lt_u32 s15, 8
	v_lshl_add_u32 v100, v0, 1, 0
	s_waitcnt lgkmcnt(0)
	s_barrier
	s_cbranch_scc1 .LBB0_559
	ds_read_b128 v[2:5], v100 offset:32256
	ds_read_b128 v[6:9], v100 offset:32288
	ds_read_b128 v[10:13], v100 offset:32320
	ds_read_b128 v[50:53], v100 offset:32352
	s_waitcnt lgkmcnt(3)
	v_mfma_f32_32x32x16_bf16 v[18:33], v[2:5], v[82:85], 0
	s_mov_b64 s[2:3], -1
	s_cmpk_lt_u32 s79, 0x41
	s_waitcnt lgkmcnt(2)
	v_mfma_f32_32x32x16_bf16 v[18:33], v[6:9], v[86:89], v[18:33]
	s_waitcnt lgkmcnt(1)
	v_mfma_f32_32x32x16_bf16 v[18:33], v[10:13], v[90:93], v[18:33]
	s_waitcnt lgkmcnt(0)
	v_mfma_f32_32x32x16_bf16 v[18:33], v[50:53], v[94:97], v[18:33]
	s_cbranch_scc1 .LBB0_553
	s_nop 10
	v_pk_fma_f32 v[16:17], v[48:49], s[84:85], v[32:33] op_sel_hi:[1,0,1]
	v_pk_fma_f32 v[14:15], v[46:47], s[84:85], v[30:31] op_sel_hi:[1,0,1]
	v_pk_fma_f32 v[12:13], v[44:45], s[84:85], v[28:29] op_sel_hi:[1,0,1]
	v_pk_fma_f32 v[10:11], v[42:43], s[84:85], v[26:27] op_sel_hi:[1,0,1]
	v_pk_fma_f32 v[8:9], v[40:41], s[84:85], v[24:25] op_sel_hi:[1,0,1]
	v_pk_fma_f32 v[6:7], v[38:39], s[84:85], v[22:23] op_sel_hi:[1,0,1]
	v_pk_fma_f32 v[4:5], v[36:37], s[84:85], v[20:21] op_sel_hi:[1,0,1]
	v_pk_fma_f32 v[2:3], v[34:35], s[84:85], v[18:19] op_sel_hi:[1,0,1]
	s_mov_b64 s[2:3], 0

.LBB0_744:
	v_readfirstlane_b32 s2, v246
	v_readlane_b32 s0, v249, 3
	v_readlane_b32 s1, v249, 4
	s_cmp_eq_u32 s2, 0
	s_cbranch_scc1 .Llwp_b_end
	s_waitcnt vmcnt(0)
	s_cmp_eq_u32 s2, 3
	s_cbranch_scc0 .Llwp_b_nos
	v_mul_f32_e32 v204, v236, v204
	v_mul_f32_e32 v205, v236, v205
	v_mul_f32_e32 v206, v236, v206
	v_mul_f32_e32 v207, v236, v207
	v_mul_f32_e32 v208, v237, v208
	v_mul_f32_e32 v209, v237, v209
	v_mul_f32_e32 v210, v237, v210
	v_mul_f32_e32 v211, v237, v211
	v_mul_f32_e32 v212, v238, v212
	v_mul_f32_e32 v213, v238, v213
	v_mul_f32_e32 v214, v238, v214
	v_mul_f32_e32 v215, v238, v215
	v_mul_f32_e32 v216, v239, v216
	v_mul_f32_e32 v217, v239, v217
	v_mul_f32_e32 v218, v239, v218
	v_mul_f32_e32 v219, v239, v219
	v_mul_f32_e32 v220, v240, v220
	v_mul_f32_e32 v221, v240, v221
	v_mul_f32_e32 v222, v240, v222
	v_mul_f32_e32 v223, v240, v223
	v_mul_f32_e32 v224, v241, v224
	v_mul_f32_e32 v225, v241, v225
	v_mul_f32_e32 v226, v241, v226
	v_mul_f32_e32 v227, v241, v227
	v_mul_f32_e32 v228, v242, v228
	v_mul_f32_e32 v229, v242, v229
	v_mul_f32_e32 v230, v242, v230
	v_mul_f32_e32 v231, v242, v231
	v_mul_f32_e32 v232, v243, v232
	v_mul_f32_e32 v233, v243, v233
	v_mul_f32_e32 v234, v243, v234
	v_mul_f32_e32 v235, v243, v235
.Llwp_b_nos:
	s_nop 1
	v_permlane32_swap_b32_e32 v204, v206
	v_permlane32_swap_b32_e32 v205, v207
	v_permlane32_swap_b32_e32 v208, v210
	v_permlane32_swap_b32_e32 v209, v211
	v_permlane32_swap_b32_e32 v212, v214
	v_permlane32_swap_b32_e32 v213, v215
	v_permlane32_swap_b32_e32 v216, v218
	v_permlane32_swap_b32_e32 v217, v219
	v_permlane32_swap_b32_e32 v220, v222
	v_permlane32_swap_b32_e32 v221, v223
	v_permlane32_swap_b32_e32 v224, v226
	v_permlane32_swap_b32_e32 v225, v227
	v_permlane32_swap_b32_e32 v228, v230
	v_permlane32_swap_b32_e32 v229, v231
	v_permlane32_swap_b32_e32 v232, v234
	v_permlane32_swap_b32_e32 v233, v235
	s_nop 1
	v_permlane16_swap_b32_e32 v204, v205
	v_permlane16_swap_b32_e32 v206, v207
	v_permlane16_swap_b32_e32 v208, v209
	v_permlane16_swap_b32_e32 v210, v211
	v_permlane16_swap_b32_e32 v212, v213
	v_permlane16_swap_b32_e32 v214, v215
	v_permlane16_swap_b32_e32 v216, v217
	v_permlane16_swap_b32_e32 v218, v219
	v_permlane16_swap_b32_e32 v220, v221
	v_permlane16_swap_b32_e32 v222, v223
	v_permlane16_swap_b32_e32 v224, v225
	v_permlane16_swap_b32_e32 v226, v227
	v_permlane16_swap_b32_e32 v228, v229
	v_permlane16_swap_b32_e32 v230, v231
	v_permlane16_swap_b32_e32 v232, v233
	v_permlane16_swap_b32_e32 v234, v235
	s_nop 1
	v_cvt_pk_bf16_f32 v204, v204, v205
	v_cvt_pk_bf16_f32 v205, v206, v207
	v_cvt_pk_bf16_f32 v206, v208, v209
	v_cvt_pk_bf16_f32 v207, v210, v211
	v_cvt_pk_bf16_f32 v208, v212, v213
	v_cvt_pk_bf16_f32 v209, v214, v215
	v_cvt_pk_bf16_f32 v210, v216, v217
	v_cvt_pk_bf16_f32 v211, v218, v219
	v_cvt_pk_bf16_f32 v212, v220, v221
	v_cvt_pk_bf16_f32 v213, v222, v223
	v_cvt_pk_bf16_f32 v214, v224, v225
	v_cvt_pk_bf16_f32 v215, v226, v227
	v_cvt_pk_bf16_f32 v216, v228, v229
	v_cvt_pk_bf16_f32 v217, v230, v231
	v_cvt_pk_bf16_f32 v218, v232, v233
	v_cvt_pk_bf16_f32 v219, v234, v235
	global_store_dwordx4 v244, v[204:207], s[0:1]
	global_store_dwordx4 v244, v[208:211], s[0:1] offset:16
	global_store_dwordx4 v244, v[212:215], s[0:1] offset:32
	global_store_dwordx4 v244, v[216:219], s[0:1] offset:48
